# rows phase dt projection: packed even/odd-channel accumulators (v_pk_fma_f32), 2 packed ops per output and slice instead of mul+3 fmac+add
# baseline (speedup 1.0000x reference)
.LBB0_464:
	v_readlane_b32 s2, v254, 27
	v_readlane_b32 s3, v254, 28
	s_andn2_b64 vcc, exec, s[2:3]
	s_nop 0
	v_cndmask_b32_e64 v84, 0, 1, s[2:3]
	v_cmp_ne_u32_e64 s[48:49], 1, v84
	s_cbranch_vccnz .LBB0_468
	s_waitcnt vmcnt(10)
	v_mov_b32_e32 v86, v5
	v_mov_b32_e32 v87, v1
	v_mov_b32_e32 v84, v4
	v_mov_b32_e32 v85, v0
	v_pk_mul_f32 v[86:87], v[86:87], v[86:87]
	s_waitcnt vmcnt(8)
	v_mov_b32_e32 v88, v15
	v_pk_fma_f32 v[84:85], v[84:85], v[84:85], v[86:87]
	v_mov_b32_e32 v86, v6
	v_mov_b32_e32 v87, v2
	v_pk_fma_f32 v[84:85], v[86:87], v[86:87], v[84:85]
	v_mov_b32_e32 v86, v7
	v_mov_b32_e32 v87, v3
	v_mov_b32_e32 v89, v11
	v_pk_fma_f32 v[84:85], v[86:87], v[86:87], v[84:85]
	v_mov_b32_e32 v86, v14
	v_mov_b32_e32 v87, v10
	v_pk_mul_f32 v[88:89], v[88:89], v[88:89]
	v_add_f32_e32 v84, v84, v85
	v_pk_fma_f32 v[86:87], v[86:87], v[86:87], v[88:89]
	v_mov_b32_e32 v88, v16
	v_mov_b32_e32 v89, v12
	v_pk_fma_f32 v[86:87], v[88:89], v[88:89], v[86:87]
	v_mov_b32_e32 v88, v17
	v_mov_b32_e32 v89, v13
	v_pk_fma_f32 v[86:87], v[88:89], v[88:89], v[86:87]
	v_add_f32_e32 v84, v87, v84
	v_add_f32_e32 v84, v86, v84
	s_mov_b32 s2, 0x800000
	s_and_b32 s1, s1, 0xfffff000
	ds_bpermute_b32 v86, v249, v84
	v_add_u32_e32 v98, s1, v101
	ds_read_b128 v[104:107], v98
	v_readlane_b32 s60, v251, 10
	v_readlane_b32 s62, v251, 12
	s_waitcnt lgkmcnt(1)
	v_add_f32_e32 v84, v84, v86
	v_readlane_b32 s63, v251, 13
	v_readlane_b32 s61, v251, 11
	ds_bpermute_b32 v86, v248, v84
	s_waitcnt lgkmcnt(0)
	v_add_f32_e32 v84, v84, v86
	s_nop 1
	ds_bpermute_b32 v86, v247, v84
	s_waitcnt lgkmcnt(0)
	v_add_f32_e32 v84, v84, v86
	s_nop 1
	ds_bpermute_b32 v86, v246, v84
	s_waitcnt lgkmcnt(0)
	v_add_f32_e32 v84, v84, v86
	s_nop 1
	ds_bpermute_b32 v86, v245, v84
	s_waitcnt lgkmcnt(0)
	v_add_f32_e32 v84, v84, v86
	s_nop 1
	ds_bpermute_b32 v85, v244, v84
	ds_read_b128 v[86:89], v100 offset:36864
	s_waitcnt lgkmcnt(1)
	v_add_f32_e32 v84, v84, v85
	v_fmamk_f32 v84, v84, 0x3a800000, v218
	v_cmp_gt_f32_e32 vcc, s2, v84
	v_mul_f32_e32 v85, 0x4b800000, v84
	s_nop 0
	v_cndmask_b32_e32 v84, v84, v85, vcc
	v_rsq_f32_e32 v84, v84
	s_nop 0
	v_mul_f32_e32 v85, 0x45800000, v84
	v_cndmask_b32_e32 v84, v84, v85, vcc
	v_add_u32_e32 v85, s1, v102
	ds_read_b128 v[108:111], v85
	v_pk_mul_f32 v[90:91], v[0:1], v[84:85] op_sel_hi:[1,0]
	s_mov_b32 s1, 0xb00000
	s_waitcnt lgkmcnt(1)
	v_pk_mul_f32 v[86:87], v[86:87], v[90:91]
	v_pk_add_f32 v[90:91], v[104:105], 1.0 op_sel_hi:[1,0]
	v_pk_mul_f32 v[118:119], v[4:5], v[84:85] op_sel_hi:[1,0]
	s_waitcnt lgkmcnt(0)
	v_pk_fma_f32 v[112:113], v[90:91], v[86:87], v[108:109]
	v_pk_mul_f32 v[86:87], v[2:3], v[84:85] op_sel_hi:[1,0]
	s_nop 0
	v_pk_mul_f32 v[86:87], v[88:89], v[86:87]
	v_pk_add_f32 v[88:89], v[106:107], 1.0 op_sel_hi:[1,0]
	s_nop 0
	v_pk_fma_f32 v[110:111], v[88:89], v[86:87], v[110:111]
	v_lshl_add_u64 v[86:87], s[62:63], 0, v[70:71]
	v_add_co_u32_e32 v86, vcc, s1, v86
	v_cvt_pk_bf16_f32 v88, v112, v113
	v_cvt_pk_bf16_f32 v89, v110, v111
	v_addc_co_u32_e32 v87, vcc, 0, v87, vcc
	global_store_dwordx2 v[86:87], v[88:89], off
	ds_read_b128 v[88:91], v100
	s_waitcnt lgkmcnt(0)
	v_pk_mul_f32 v[228:229], v[112:113], v[88:89]
	v_pk_fma_f32 v[228:229], v[110:111], v[90:91], v[228:229]
	ds_read_b128 v[88:91], v100 offset:4096
	s_waitcnt lgkmcnt(0)
	v_pk_mul_f32 v[230:231], v[112:113], v[88:89]
	v_pk_fma_f32 v[230:231], v[110:111], v[90:91], v[230:231]
	ds_read_b128 v[88:91], v100 offset:8192
	s_waitcnt lgkmcnt(0)
	v_pk_mul_f32 v[232:233], v[112:113], v[88:89]
	v_pk_fma_f32 v[232:233], v[110:111], v[90:91], v[232:233]
	ds_read_b128 v[88:91], v100 offset:12288
	s_waitcnt lgkmcnt(0)
	v_pk_mul_f32 v[234:235], v[112:113], v[88:89]
	v_pk_fma_f32 v[234:235], v[110:111], v[90:91], v[234:235]
	ds_read_b128 v[88:91], v100 offset:16384
	s_waitcnt lgkmcnt(0)
	v_pk_mul_f32 v[236:237], v[112:113], v[88:89]
	v_pk_fma_f32 v[236:237], v[110:111], v[90:91], v[236:237]
	ds_read_b128 v[88:91], v100 offset:20480
	s_waitcnt lgkmcnt(0)
	v_pk_mul_f32 v[238:239], v[112:113], v[88:89]
	v_pk_fma_f32 v[238:239], v[110:111], v[90:91], v[238:239]
	ds_read_b128 v[88:91], v100 offset:24576
	s_waitcnt lgkmcnt(0)
	v_pk_mul_f32 v[240:241], v[112:113], v[88:89]
	v_pk_fma_f32 v[240:241], v[110:111], v[90:91], v[240:241]
	ds_read_b128 v[88:91], v100 offset:28672
	s_waitcnt lgkmcnt(0)
	v_pk_mul_f32 v[242:243], v[112:113], v[88:89]
	v_pk_fma_f32 v[242:243], v[110:111], v[90:91], v[242:243]
	ds_read_b128 v[88:91], v100 offset:37888
	ds_read_b128 v[110:113], v98 offset:1024
	ds_read_b128 v[114:117], v85 offset:1024
	s_waitcnt lgkmcnt(2)
	v_pk_mul_f32 v[88:89], v[118:119], v[88:89]
	s_waitcnt lgkmcnt(1)
	v_pk_add_f32 v[110:111], v[110:111], 1.0 op_sel_hi:[1,0]
	s_waitcnt lgkmcnt(0)
	v_pk_fma_f32 v[88:89], v[88:89], v[110:111], v[114:115]
	v_pk_mul_f32 v[110:111], v[6:7], v[84:85] op_sel_hi:[1,0]
	s_nop 0
	v_pk_mul_f32 v[90:91], v[110:111], v[90:91]
	v_pk_add_f32 v[110:111], v[112:113], 1.0 op_sel_hi:[1,0]
	s_nop 0
	v_pk_fma_f32 v[90:91], v[90:91], v[110:111], v[116:117]
	v_cvt_pk_bf16_f32 v110, v88, v89
	v_cvt_pk_bf16_f32 v111, v90, v91
	global_store_dwordx2 v[86:87], v[110:111], off offset:512
	ds_read_b128 v[110:113], v100 offset:1024
	s_waitcnt lgkmcnt(0)
	v_pk_fma_f32 v[228:229], v[88:89], v[110:111], v[228:229]
	v_pk_fma_f32 v[228:229], v[90:91], v[112:113], v[228:229]
	ds_read_b128 v[110:113], v100 offset:5120
	s_waitcnt lgkmcnt(0)
	v_pk_fma_f32 v[230:231], v[88:89], v[110:111], v[230:231]
	v_pk_fma_f32 v[230:231], v[90:91], v[112:113], v[230:231]
	ds_read_b128 v[110:113], v100 offset:9216
	s_waitcnt lgkmcnt(0)
	v_pk_fma_f32 v[232:233], v[88:89], v[110:111], v[232:233]
	v_pk_fma_f32 v[232:233], v[90:91], v[112:113], v[232:233]
	ds_read_b128 v[108:111], v100 offset:13312
	s_waitcnt lgkmcnt(0)
	v_pk_fma_f32 v[234:235], v[88:89], v[108:109], v[234:235]
	v_pk_fma_f32 v[234:235], v[90:91], v[110:111], v[234:235]
	ds_read_b128 v[108:111], v100 offset:17408
	s_waitcnt lgkmcnt(0)
	v_pk_fma_f32 v[236:237], v[88:89], v[108:109], v[236:237]
	v_pk_fma_f32 v[236:237], v[90:91], v[110:111], v[236:237]
	ds_read_b128 v[108:111], v100 offset:21504
	s_waitcnt lgkmcnt(0)
	v_pk_fma_f32 v[238:239], v[88:89], v[108:109], v[238:239]
	v_pk_fma_f32 v[238:239], v[90:91], v[110:111], v[238:239]
	ds_read_b128 v[108:111], v100 offset:25600
	s_waitcnt lgkmcnt(0)
	v_pk_fma_f32 v[240:241], v[88:89], v[108:109], v[240:241]
	v_pk_fma_f32 v[240:241], v[90:91], v[110:111], v[240:241]
	ds_read_b128 v[108:111], v100 offset:29696
	v_pk_mul_f32 v[104:105], v[10:11], v[84:85] op_sel_hi:[1,0]
	s_waitcnt lgkmcnt(0)
	v_pk_fma_f32 v[242:243], v[88:89], v[108:109], v[242:243]
	v_pk_fma_f32 v[242:243], v[90:91], v[110:111], v[242:243]
	ds_read_b128 v[88:91], v100 offset:38912
	ds_read_b128 v[108:111], v98 offset:2048
	ds_read_b128 v[112:115], v85 offset:2048
	s_waitcnt lgkmcnt(2)
	v_pk_mul_f32 v[88:89], v[104:105], v[88:89]
	s_waitcnt lgkmcnt(1)
	v_pk_add_f32 v[104:105], v[108:109], 1.0 op_sel_hi:[1,0]
	s_waitcnt lgkmcnt(0)
	v_pk_fma_f32 v[112:113], v[88:89], v[104:105], v[112:113]
	v_pk_mul_f32 v[88:89], v[12:13], v[84:85] op_sel_hi:[1,0]
	s_nop 0
	v_pk_mul_f32 v[88:89], v[88:89], v[90:91]
	v_pk_add_f32 v[90:91], v[110:111], 1.0 op_sel_hi:[1,0]
	s_nop 0
	v_pk_fma_f32 v[110:111], v[88:89], v[90:91], v[114:115]
	v_cvt_pk_bf16_f32 v88, v112, v113
	v_cvt_pk_bf16_f32 v89, v110, v111
	global_store_dwordx2 v[86:87], v[88:89], off offset:1024
	ds_read_b128 v[88:91], v100 offset:2048
	s_waitcnt lgkmcnt(0)
	v_pk_fma_f32 v[228:229], v[112:113], v[88:89], v[228:229]
	v_pk_fma_f32 v[228:229], v[110:111], v[90:91], v[228:229]
	ds_read_b128 v[88:91], v100 offset:6144
	s_waitcnt lgkmcnt(0)
	v_pk_fma_f32 v[230:231], v[112:113], v[88:89], v[230:231]
	v_pk_fma_f32 v[230:231], v[110:111], v[90:91], v[230:231]
	ds_read_b128 v[88:91], v100 offset:10240
	s_waitcnt lgkmcnt(0)
	v_pk_fma_f32 v[232:233], v[112:113], v[88:89], v[232:233]
	v_pk_fma_f32 v[232:233], v[110:111], v[90:91], v[232:233]
	ds_read_b128 v[88:91], v100 offset:14336
	s_waitcnt lgkmcnt(0)
	v_pk_fma_f32 v[234:235], v[112:113], v[88:89], v[234:235]
	v_pk_fma_f32 v[234:235], v[110:111], v[90:91], v[234:235]
	ds_read_b128 v[88:91], v100 offset:18432
	ds_read_b128 v[106:109], v100 offset:30720
	s_waitcnt lgkmcnt(1)
	v_pk_fma_f32 v[236:237], v[112:113], v[88:89], v[236:237]
	v_pk_fma_f32 v[236:237], v[110:111], v[90:91], v[236:237]
	ds_read_b128 v[88:91], v100 offset:22528
	s_waitcnt lgkmcnt(0)
	v_pk_fma_f32 v[238:239], v[112:113], v[88:89], v[238:239]
	v_pk_fma_f32 v[238:239], v[110:111], v[90:91], v[238:239]
	ds_read_b128 v[88:91], v100 offset:26624
	s_waitcnt lgkmcnt(0)
	v_pk_fma_f32 v[240:241], v[112:113], v[88:89], v[240:241]
	v_pk_fma_f32 v[242:243], v[112:113], v[106:107], v[242:243]
	v_pk_fma_f32 v[240:241], v[110:111], v[90:91], v[240:241]
	v_pk_fma_f32 v[242:243], v[110:111], v[108:109], v[242:243]
	ds_read_b128 v[106:109], v100 offset:39936
	ds_read_b128 v[110:113], v98 offset:3072
	ds_read_b128 v[114:117], v85 offset:3072
	v_pk_mul_f32 v[88:89], v[14:15], v[84:85] op_sel_hi:[1,0]
	v_pk_mul_f32 v[84:85], v[16:17], v[84:85] op_sel_hi:[1,0]
	s_waitcnt lgkmcnt(2)
	v_pk_mul_f32 v[88:89], v[88:89], v[106:107]
	s_waitcnt lgkmcnt(1)
	v_pk_add_f32 v[106:107], v[110:111], 1.0 op_sel_hi:[1,0]
	v_pk_mul_f32 v[84:85], v[84:85], v[108:109]
	s_waitcnt lgkmcnt(0)
	v_pk_fma_f32 v[88:89], v[88:89], v[106:107], v[114:115]
	v_pk_add_f32 v[106:107], v[112:113], 1.0 op_sel_hi:[1,0]
	s_nop 0
	v_pk_fma_f32 v[84:85], v[84:85], v[106:107], v[116:117]
	v_cvt_pk_bf16_f32 v106, v88, v89
	v_cvt_pk_bf16_f32 v107, v84, v85
	global_store_dwordx2 v[86:87], v[106:107], off offset:1536
	ds_read_b128 v[106:109], v100 offset:3072
	s_waitcnt lgkmcnt(0)
	v_pk_fma_f32 v[228:229], v[88:89], v[106:107], v[228:229]
	v_pk_fma_f32 v[228:229], v[84:85], v[108:109], v[228:229]
	ds_read_b128 v[106:109], v100 offset:7168
	v_add_f32_e32 v86, v228, v229
	s_waitcnt lgkmcnt(0)
	v_pk_fma_f32 v[230:231], v[88:89], v[106:107], v[230:231]
	v_pk_fma_f32 v[230:231], v[84:85], v[108:109], v[230:231]
	ds_read_b128 v[106:109], v100 offset:11264
	v_add_f32_e32 v87, v230, v231
	s_waitcnt lgkmcnt(0)
	v_pk_fma_f32 v[232:233], v[88:89], v[106:107], v[232:233]
	v_pk_fma_f32 v[232:233], v[84:85], v[108:109], v[232:233]
	ds_read_b128 v[106:109], v100 offset:15360
	v_add_f32_e32 v98, v232, v233
	s_waitcnt lgkmcnt(0)
	v_pk_fma_f32 v[234:235], v[88:89], v[106:107], v[234:235]
	v_pk_fma_f32 v[234:235], v[84:85], v[108:109], v[234:235]
	v_add_f32_e32 v108, v234, v235
	ds_read_b128 v[104:107], v100 offset:19456
	s_waitcnt lgkmcnt(0)
	v_pk_fma_f32 v[236:237], v[88:89], v[104:105], v[236:237]
	v_pk_fma_f32 v[236:237], v[84:85], v[106:107], v[236:237]
	v_add_f32_e32 v103, v236, v237
	ds_read_b128 v[104:107], v100 offset:23552
	s_waitcnt lgkmcnt(0)
	v_pk_fma_f32 v[238:239], v[88:89], v[104:105], v[238:239]
	v_pk_fma_f32 v[238:239], v[84:85], v[106:107], v[238:239]
	v_add_f32_e32 v99, v238, v239
	ds_read_b128 v[104:107], v100 offset:27648
	s_waitcnt lgkmcnt(0)
	v_pk_fma_f32 v[240:241], v[88:89], v[104:105], v[240:241]
	v_pk_fma_f32 v[240:241], v[84:85], v[106:107], v[240:241]
	v_add_f32_e32 v91, v240, v241
	ds_read_b128 v[104:107], v100 offset:31744
	s_waitcnt lgkmcnt(0)
	v_pk_fma_f32 v[242:243], v[88:89], v[104:105], v[242:243]
	v_pk_fma_f32 v[242:243], v[84:85], v[106:107], v[242:243]
	v_cndmask_b32_e64 v85, v103, v86, s[40:41]
	v_cndmask_b32_e64 v86, v86, v103, s[40:41]
	ds_bpermute_b32 v86, v249, v86
	v_cndmask_b32_e64 v88, v98, v91, s[40:41]
	ds_bpermute_b32 v88, v249, v88
	v_add_f32_e32 v84, v242, v243
	s_waitcnt lgkmcnt(1)
	v_add_f32_e32 v85, v85, v86
	v_cndmask_b32_e64 v86, v99, v87, s[40:41]
	v_cndmask_b32_e64 v87, v87, v99, s[40:41]
	ds_bpermute_b32 v87, v249, v87
	s_waitcnt lgkmcnt(0)
	v_add_f32_e32 v86, v86, v87
	v_cndmask_b32_e64 v87, v91, v98, s[40:41]
	v_add_f32_e32 v87, v87, v88
	v_cndmask_b32_e64 v88, v84, v108, s[40:41]
	v_cndmask_b32_e64 v84, v108, v84, s[40:41]
	ds_bpermute_b32 v84, v249, v84
	s_waitcnt lgkmcnt(0)
	v_add_f32_e32 v84, v88, v84
	v_cndmask_b32_e64 v88, v87, v85, s[42:43]
	v_cndmask_b32_e64 v85, v85, v87, s[42:43]
	v_cndmask_b32_e64 v87, v84, v86, s[42:43]
	v_cndmask_b32_e64 v84, v86, v84, s[42:43]
	ds_bpermute_b32 v85, v248, v85
	ds_bpermute_b32 v84, v248, v84
	s_waitcnt lgkmcnt(1)
	v_add_f32_e32 v85, v88, v85
	s_waitcnt lgkmcnt(0)
	v_add_f32_e32 v84, v87, v84
	v_cndmask_b32_e64 v86, v84, v85, s[44:45]
	v_cndmask_b32_e64 v84, v85, v84, s[44:45]
	ds_bpermute_b32 v84, v247, v84
	s_waitcnt lgkmcnt(0)
	v_add_f32_e32 v84, v86, v84
	ds_bpermute_b32 v85, v246, v84
	s_waitcnt lgkmcnt(0)
	v_add_f32_e32 v84, v84, v85
	ds_bpermute_b32 v85, v245, v84
	s_waitcnt lgkmcnt(0)
	v_add_f32_e32 v84, v84, v85
	ds_bpermute_b32 v85, v244, v84
	s_and_saveexec_b64 s[18:19], s[46:47]
	s_cbranch_execz .LBB0_467
	v_readlane_b32 s60, v251, 10
	v_readlane_b32 s62, v251, 12
	v_readlane_b32 s63, v251, 13
	s_waitcnt lgkmcnt(0)
	v_add_f32_e32 v86, v84, v85
	v_readlane_b32 s61, v251, 11
	v_lshl_add_u64 v[84:85], s[62:63], 0, v[68:69]
	global_store_dword v[84:85], v86, off

.LBB0_487:
	s_waitcnt vmcnt(10)
	v_mov_b32_e32 v86, v23
	v_mov_b32_e32 v87, v19
	v_mov_b32_e32 v84, v22
	v_mov_b32_e32 v85, v18
	v_pk_mul_f32 v[86:87], v[86:87], v[86:87]
	s_waitcnt vmcnt(8)
	v_mov_b32_e32 v88, v31
	v_pk_fma_f32 v[84:85], v[84:85], v[84:85], v[86:87]
	v_mov_b32_e32 v86, v24
	v_mov_b32_e32 v87, v20
	v_pk_fma_f32 v[84:85], v[86:87], v[86:87], v[84:85]
	v_mov_b32_e32 v86, v25
	v_mov_b32_e32 v87, v21
	v_mov_b32_e32 v89, v27
	v_pk_fma_f32 v[84:85], v[86:87], v[86:87], v[84:85]
	v_mov_b32_e32 v86, v30
	v_mov_b32_e32 v87, v26
	v_pk_mul_f32 v[88:89], v[88:89], v[88:89]
	v_add_f32_e32 v84, v84, v85
	v_pk_fma_f32 v[86:87], v[86:87], v[86:87], v[88:89]
	v_mov_b32_e32 v88, v32
	v_mov_b32_e32 v89, v28
	v_pk_fma_f32 v[86:87], v[88:89], v[88:89], v[86:87]
	v_mov_b32_e32 v88, v33
	v_mov_b32_e32 v89, v29
	v_pk_fma_f32 v[86:87], v[88:89], v[88:89], v[86:87]
	v_add_f32_e32 v84, v87, v84
	v_add_f32_e32 v84, v86, v84
	s_mov_b32 s2, 0x800000
	s_and_b32 s1, s1, 0xfffff000
	ds_bpermute_b32 v86, v249, v84
	v_add_u32_e32 v98, s1, v101
	ds_read_b128 v[94:97], v98
	v_add_u32_e32 v93, s1, v102
	ds_read_b128 v[110:113], v93
	s_waitcnt lgkmcnt(2)
	v_add_f32_e32 v84, v84, v86
	s_ashr_i32 s57, s56, 31
	ds_read_b128 v[114:117], v100
	ds_bpermute_b32 v86, v248, v84
	s_waitcnt lgkmcnt(0)
	v_add_f32_e32 v84, v84, v86
	s_nop 1
	ds_bpermute_b32 v86, v247, v84
	s_waitcnt lgkmcnt(0)
	v_add_f32_e32 v84, v84, v86
	s_nop 1
	ds_bpermute_b32 v86, v246, v84
	s_waitcnt lgkmcnt(0)
	v_add_f32_e32 v84, v84, v86
	s_nop 1
	ds_bpermute_b32 v86, v245, v84
	s_waitcnt lgkmcnt(0)
	v_add_f32_e32 v84, v84, v86
	s_nop 1
	ds_bpermute_b32 v85, v244, v84
	ds_read_b128 v[86:89], v100 offset:36864
	s_waitcnt lgkmcnt(1)
	v_add_f32_e32 v84, v84, v85
	v_fmamk_f32 v84, v84, 0x3a800000, v218
	v_cmp_gt_f32_e32 vcc, s2, v84
	v_mul_f32_e32 v85, 0x4b800000, v84
	s_lshl_b64 s[2:3], s[56:57], 11
	v_cndmask_b32_e32 v84, v84, v85, vcc
	v_rsq_f32_e32 v84, v84
	s_nop 0
	v_mul_f32_e32 v85, 0x45800000, v84
	v_cndmask_b32_e32 v92, v84, v85, vcc
	v_pk_mul_f32 v[84:85], v[18:19], v[92:93] op_sel_hi:[1,0]
	v_pk_mul_f32 v[118:119], v[22:23], v[92:93] op_sel_hi:[1,0]
	s_waitcnt lgkmcnt(0)
	v_pk_mul_f32 v[84:85], v[86:87], v[84:85]
	v_pk_add_f32 v[86:87], v[94:95], 1.0 op_sel_hi:[1,0]
	s_nop 0
	v_pk_fma_f32 v[86:87], v[86:87], v[84:85], v[110:111]
	v_pk_mul_f32 v[84:85], v[20:21], v[92:93] op_sel_hi:[1,0]
	v_pk_mul_f32 v[84:85], v[88:89], v[84:85]
	v_pk_add_f32 v[88:89], v[96:97], 1.0 op_sel_hi:[1,0]
	v_pk_mul_f32 v[228:229], v[86:87], v[114:115]
	v_pk_fma_f32 v[84:85], v[88:89], v[84:85], v[112:113]
	ds_read_b128 v[88:91], v100 offset:4096
	v_pk_fma_f32 v[228:229], v[84:85], v[116:117], v[228:229]
	ds_read_b128 v[94:97], v100 offset:8192
	s_waitcnt lgkmcnt(1)
	v_pk_mul_f32 v[230:231], v[86:87], v[88:89]
	v_pk_fma_f32 v[230:231], v[84:85], v[90:91], v[230:231]
	ds_read_b128 v[88:91], v100 offset:12288
	s_waitcnt lgkmcnt(1)
	v_pk_mul_f32 v[232:233], v[86:87], v[94:95]
	v_pk_fma_f32 v[232:233], v[84:85], v[96:97], v[232:233]
	ds_read_b128 v[94:97], v100 offset:16384
	s_waitcnt lgkmcnt(1)
	v_pk_mul_f32 v[234:235], v[86:87], v[88:89]
	v_pk_fma_f32 v[234:235], v[84:85], v[90:91], v[234:235]
	ds_read_b128 v[88:91], v100 offset:20480
	ds_read_b128 v[110:113], v100 offset:24576
	s_waitcnt lgkmcnt(2)
	v_pk_mul_f32 v[236:237], v[86:87], v[94:95]
	s_waitcnt lgkmcnt(1)
	v_pk_mul_f32 v[238:239], v[86:87], v[88:89]
	v_pk_fma_f32 v[236:237], v[84:85], v[96:97], v[236:237]
	v_pk_fma_f32 v[238:239], v[84:85], v[90:91], v[238:239]
	ds_read_b128 v[88:91], v100 offset:28672
	s_waitcnt lgkmcnt(1)
	v_pk_mul_f32 v[240:241], v[86:87], v[110:111]
	v_pk_fma_f32 v[240:241], v[84:85], v[112:113], v[240:241]
	s_waitcnt lgkmcnt(0)
	v_pk_mul_f32 v[242:243], v[86:87], v[88:89]
	v_pk_fma_f32 v[242:243], v[84:85], v[90:91], v[242:243]
	ds_read_b128 v[88:91], v100 offset:37888
	ds_read_b128 v[110:113], v98 offset:1024
	ds_read_b128 v[114:117], v93 offset:1024
	s_waitcnt lgkmcnt(2)
	v_pk_mul_f32 v[88:89], v[118:119], v[88:89]
	ds_read_b128 v[118:121], v100 offset:1024
	s_waitcnt lgkmcnt(2)
	v_pk_add_f32 v[110:111], v[110:111], 1.0 op_sel_hi:[1,0]
	v_cvt_pk_bf16_f32 v86, v86, v87
	s_waitcnt lgkmcnt(1)
	v_pk_fma_f32 v[88:89], v[88:89], v[110:111], v[114:115]
	v_pk_mul_f32 v[110:111], v[24:25], v[92:93] op_sel_hi:[1,0]
	s_nop 0
	v_pk_mul_f32 v[90:91], v[110:111], v[90:91]
	v_pk_add_f32 v[110:111], v[112:113], 1.0 op_sel_hi:[1,0]
	s_nop 0
	v_pk_fma_f32 v[90:91], v[90:91], v[110:111], v[116:117]
	ds_read_b128 v[110:113], v100 offset:5120
	s_waitcnt lgkmcnt(1)
	v_pk_fma_f32 v[228:229], v[88:89], v[118:119], v[228:229]
	v_pk_fma_f32 v[228:229], v[90:91], v[120:121], v[228:229]
	ds_read_b128 v[114:117], v100 offset:9216
	s_waitcnt lgkmcnt(1)
	v_pk_fma_f32 v[230:231], v[88:89], v[110:111], v[230:231]
	v_pk_fma_f32 v[230:231], v[90:91], v[112:113], v[230:231]
	ds_read_b128 v[110:113], v100 offset:13312
	s_waitcnt lgkmcnt(1)
	v_pk_fma_f32 v[232:233], v[88:89], v[114:115], v[232:233]
	v_pk_fma_f32 v[232:233], v[90:91], v[116:117], v[232:233]
	ds_read_b128 v[114:117], v100 offset:17408
	s_waitcnt lgkmcnt(1)
	v_pk_fma_f32 v[234:235], v[88:89], v[110:111], v[234:235]
	v_pk_fma_f32 v[234:235], v[90:91], v[112:113], v[234:235]
	ds_read_b128 v[110:113], v100 offset:21504
	s_waitcnt lgkmcnt(1)
	v_pk_fma_f32 v[236:237], v[88:89], v[114:115], v[236:237]
	v_pk_fma_f32 v[236:237], v[90:91], v[116:117], v[236:237]
	ds_read_b128 v[114:117], v100 offset:25600
	s_waitcnt lgkmcnt(1)
	v_pk_fma_f32 v[238:239], v[88:89], v[110:111], v[238:239]
	v_pk_fma_f32 v[238:239], v[90:91], v[112:113], v[238:239]
	ds_read_b128 v[110:113], v100 offset:29696
	s_waitcnt lgkmcnt(1)
	v_pk_fma_f32 v[240:241], v[88:89], v[114:115], v[240:241]
	v_pk_fma_f32 v[240:241], v[90:91], v[116:117], v[240:241]
	s_waitcnt lgkmcnt(0)
	v_pk_fma_f32 v[242:243], v[88:89], v[110:111], v[242:243]
	v_pk_fma_f32 v[242:243], v[90:91], v[112:113], v[242:243]
	ds_read_b128 v[110:113], v100 offset:38912
	ds_read_b128 v[114:117], v98 offset:2048
	ds_read_b128 v[118:121], v93 offset:2048
	ds_read_b128 v[122:125], v100 offset:2048
	v_pk_mul_f32 v[94:95], v[26:27], v[92:93] op_sel_hi:[1,0]
	s_waitcnt lgkmcnt(2)
	v_pk_add_f32 v[96:97], v[114:115], 1.0 op_sel_hi:[1,0]
	v_pk_mul_f32 v[94:95], v[94:95], v[110:111]
	v_pk_add_f32 v[110:111], v[116:117], 1.0 op_sel_hi:[1,0]
	s_waitcnt lgkmcnt(1)
	v_pk_fma_f32 v[94:95], v[94:95], v[96:97], v[118:119]
	v_pk_mul_f32 v[96:97], v[28:29], v[92:93] op_sel_hi:[1,0]
	s_nop 0
	v_pk_mul_f32 v[96:97], v[96:97], v[112:113]
	s_nop 0
	v_pk_fma_f32 v[96:97], v[96:97], v[110:111], v[120:121]
	ds_read_b128 v[110:113], v100 offset:6144
	s_waitcnt lgkmcnt(1)
	v_pk_fma_f32 v[228:229], v[94:95], v[122:123], v[228:229]
	v_pk_fma_f32 v[228:229], v[96:97], v[124:125], v[228:229]
	ds_read_b128 v[114:117], v100 offset:10240
	s_waitcnt lgkmcnt(1)
	v_pk_fma_f32 v[230:231], v[94:95], v[110:111], v[230:231]
	v_pk_fma_f32 v[230:231], v[96:97], v[112:113], v[230:231]
	ds_read_b128 v[110:113], v100 offset:14336
	s_waitcnt lgkmcnt(1)
	v_pk_fma_f32 v[232:233], v[94:95], v[114:115], v[232:233]
	v_pk_fma_f32 v[232:233], v[96:97], v[116:117], v[232:233]
	ds_read_b128 v[114:117], v100 offset:18432
	ds_read_b128 v[118:121], v100 offset:22528
	s_waitcnt lgkmcnt(2)
	v_pk_fma_f32 v[234:235], v[94:95], v[110:111], v[234:235]
	v_pk_fma_f32 v[234:235], v[96:97], v[112:113], v[234:235]
	s_waitcnt lgkmcnt(1)
	v_pk_fma_f32 v[236:237], v[94:95], v[114:115], v[236:237]
	v_pk_fma_f32 v[236:237], v[96:97], v[116:117], v[236:237]
	ds_read_b128 v[114:117], v100 offset:26624
	s_waitcnt lgkmcnt(1)
	v_pk_fma_f32 v[238:239], v[94:95], v[118:119], v[238:239]
	v_pk_fma_f32 v[238:239], v[96:97], v[120:121], v[238:239]
	ds_read_b128 v[118:121], v100 offset:30720
	s_waitcnt lgkmcnt(1)
	v_pk_fma_f32 v[240:241], v[94:95], v[114:115], v[240:241]
	v_pk_fma_f32 v[240:241], v[96:97], v[116:117], v[240:241]
	s_waitcnt lgkmcnt(0)
	v_pk_fma_f32 v[242:243], v[94:95], v[118:119], v[242:243]
	v_pk_fma_f32 v[242:243], v[96:97], v[120:121], v[242:243]
	ds_read_b128 v[114:117], v100 offset:39936
	ds_read_b128 v[118:121], v98 offset:3072
	ds_read_b128 v[122:125], v93 offset:3072
	v_pk_mul_f32 v[98:99], v[30:31], v[92:93] op_sel_hi:[1,0]
	v_pk_mul_f32 v[92:93], v[32:33], v[92:93] op_sel_hi:[1,0]
	s_waitcnt lgkmcnt(2)
	v_pk_mul_f32 v[98:99], v[98:99], v[114:115]
	s_waitcnt lgkmcnt(1)
	v_pk_add_f32 v[114:115], v[118:119], 1.0 op_sel_hi:[1,0]
	v_pk_mul_f32 v[92:93], v[92:93], v[116:117]
	s_waitcnt lgkmcnt(0)
	v_pk_fma_f32 v[98:99], v[98:99], v[114:115], v[122:123]
	v_pk_add_f32 v[114:115], v[120:121], 1.0 op_sel_hi:[1,0]
	ds_read_b128 v[126:129], v100 offset:3072
	v_pk_fma_f32 v[92:93], v[92:93], v[114:115], v[124:125]
	ds_read_b128 v[114:117], v100 offset:7168
	s_waitcnt lgkmcnt(1)
	v_pk_fma_f32 v[228:229], v[98:99], v[126:127], v[228:229]
	s_waitcnt lgkmcnt(0)
	v_pk_fma_f32 v[230:231], v[98:99], v[114:115], v[230:231]
	v_pk_fma_f32 v[228:229], v[92:93], v[128:129], v[228:229]
	v_pk_fma_f32 v[230:231], v[92:93], v[116:117], v[230:231]
	v_add_f32_e32 v122, v228, v229
	ds_read_b128 v[118:121], v100 offset:11264
	v_add_f32_e32 v123, v230, v231
	ds_read_b128 v[114:117], v100 offset:15360
	s_waitcnt lgkmcnt(1)
	v_pk_fma_f32 v[232:233], v[98:99], v[118:119], v[232:233]
	s_waitcnt lgkmcnt(0)
	v_pk_fma_f32 v[234:235], v[98:99], v[114:115], v[234:235]
	v_pk_fma_f32 v[232:233], v[92:93], v[120:121], v[232:233]
	v_pk_fma_f32 v[234:235], v[92:93], v[116:117], v[234:235]
	v_add_f32_e32 v124, v232, v233
	ds_read_b128 v[118:121], v100 offset:19456
	v_add_f32_e32 v113, v234, v235
	ds_read_b128 v[114:117], v100 offset:23552
	s_waitcnt lgkmcnt(1)
	v_pk_fma_f32 v[236:237], v[98:99], v[118:119], v[236:237]
	s_waitcnt lgkmcnt(0)
	v_pk_fma_f32 v[238:239], v[98:99], v[114:115], v[238:239]
	v_pk_fma_f32 v[236:237], v[92:93], v[120:121], v[236:237]
	v_pk_fma_f32 v[238:239], v[92:93], v[116:117], v[238:239]
	v_add_f32_e32 v111, v236, v237
	ds_read_b128 v[118:121], v100 offset:27648
	v_add_f32_e32 v110, v238, v239
	ds_read_b128 v[114:117], v100 offset:31744
	s_waitcnt lgkmcnt(1)
	v_pk_fma_f32 v[240:241], v[98:99], v[118:119], v[240:241]
	s_waitcnt lgkmcnt(0)
	v_pk_fma_f32 v[242:243], v[98:99], v[114:115], v[242:243]
	v_cndmask_b32_e64 v114, v122, v111, s[40:41]
	ds_bpermute_b32 v114, v249, v114
	v_pk_fma_f32 v[240:241], v[92:93], v[120:121], v[240:241]
	v_pk_fma_f32 v[242:243], v[92:93], v[116:117], v[242:243]
	v_add_f32_e32 v109, v240, v241
	v_add_f32_e32 v112, v242, v243
	v_cndmask_b32_e64 v111, v111, v122, s[40:41]
	s_waitcnt lgkmcnt(0)
	v_add_f32_e32 v111, v111, v114
	v_cndmask_b32_e64 v114, v110, v123, s[40:41]
	v_cndmask_b32_e64 v110, v123, v110, s[40:41]
	v_cndmask_b32_e64 v115, v124, v109, s[40:41]
	v_cndmask_b32_e64 v116, v113, v112, s[40:41]
	ds_bpermute_b32 v110, v249, v110
	ds_bpermute_b32 v115, v249, v115
	ds_bpermute_b32 v108, v249, v116
	v_cndmask_b32_e64 v109, v109, v124, s[40:41]
	v_cndmask_b32_e64 v112, v112, v113, s[40:41]
	s_waitcnt lgkmcnt(2)
	v_add_f32_e32 v110, v114, v110
	s_waitcnt lgkmcnt(1)
	v_add_f32_e32 v109, v109, v115
	s_waitcnt lgkmcnt(0)
	v_add_f32_e32 v108, v112, v108
	v_cndmask_b32_e64 v112, v111, v109, s[42:43]
	v_cndmask_b32_e64 v113, v110, v108, s[42:43]
	ds_bpermute_b32 v112, v248, v112
	ds_bpermute_b32 v107, v248, v113
	v_cndmask_b32_e64 v109, v109, v111, s[42:43]
	v_cndmask_b32_e64 v108, v108, v110, s[42:43]
	s_waitcnt lgkmcnt(1)
	v_add_f32_e32 v109, v109, v112
	s_waitcnt lgkmcnt(0)
	v_add_f32_e32 v107, v108, v107
	v_cndmask_b32_e64 v108, v109, v107, s[44:45]
	ds_bpermute_b32 v106, v247, v108
	v_cndmask_b32_e64 v87, v107, v109, s[44:45]
	s_waitcnt lgkmcnt(0)
	v_add_f32_e32 v108, v87, v106
	ds_bpermute_b32 v105, v246, v108
	v_cvt_pk_bf16_f32 v87, v84, v85
	v_cvt_pk_bf16_f32 v84, v88, v89
	v_lshl_add_u64 v[106:107], v[66:67], 0, s[2:3]
	v_cvt_pk_bf16_f32 v85, v90, v91
	s_waitcnt lgkmcnt(0)
	v_add_f32_e32 v88, v108, v105
	ds_bpermute_b32 v89, v245, v88
	global_store_dwordx2 v[106:107], v[84:85], off offset:512
	global_store_dwordx2 v[106:107], v[86:87], off
	v_cvt_pk_bf16_f32 v86, v94, v95
	v_cvt_pk_bf16_f32 v87, v96, v97
	s_waitcnt lgkmcnt(0)
	v_add_f32_e32 v84, v88, v89
	ds_bpermute_b32 v85, v244, v84
	global_store_dwordx2 v[106:107], v[86:87], off offset:1024
	v_cvt_pk_bf16_f32 v86, v98, v99
	v_cvt_pk_bf16_f32 v87, v92, v93
	global_store_dwordx2 v[106:107], v[86:87], off offset:1536
	s_and_saveexec_b64 s[18:19], s[46:47]
	s_cbranch_execz .LBB0_489
	s_lshl_b64 s[2:3], s[56:57], 5
	s_waitcnt lgkmcnt(0)
	v_add_f32_e32 v86, v84, v85
	v_lshl_add_u64 v[84:85], v[64:65], 0, s[2:3]
	global_store_dword v[84:85], v86, off

.LBB0_505:
	s_waitcnt vmcnt(6)
	v_mov_b32_e32 v78, v43
	v_mov_b32_e32 v79, v47
	v_mov_b32_e32 v76, v42
	v_mov_b32_e32 v77, v46
	v_pk_mul_f32 v[78:79], v[78:79], v[78:79]
	s_waitcnt vmcnt(4)
	v_mov_b32_e32 v80, v35
	v_pk_fma_f32 v[76:77], v[76:77], v[76:77], v[78:79]
	v_mov_b32_e32 v78, v44
	v_mov_b32_e32 v79, v48
	v_pk_fma_f32 v[76:77], v[78:79], v[78:79], v[76:77]
	v_mov_b32_e32 v78, v45
	v_mov_b32_e32 v79, v49
	v_mov_b32_e32 v81, v39
	v_pk_fma_f32 v[76:77], v[78:79], v[78:79], v[76:77]
	v_mov_b32_e32 v78, v34
	v_mov_b32_e32 v79, v38
	v_pk_mul_f32 v[80:81], v[80:81], v[80:81]
	v_add_f32_e32 v76, v76, v77
	v_pk_fma_f32 v[78:79], v[78:79], v[78:79], v[80:81]
	v_mov_b32_e32 v80, v36
	v_mov_b32_e32 v81, v40
	v_pk_fma_f32 v[78:79], v[80:81], v[80:81], v[78:79]
	v_mov_b32_e32 v80, v37
	v_mov_b32_e32 v81, v41
	v_pk_fma_f32 v[78:79], v[80:81], v[80:81], v[78:79]
	v_and_b32_e32 v77, 64, v220
	v_add_f32_e32 v76, v79, v76
	v_add_f32_e32 v76, v78, v76
	v_add_u32_e32 v77, 64, v77
	s_mov_b32 s2, 0x800000
	s_and_b32 s1, s1, 0xfffff000
	ds_bpermute_b32 v78, v249, v76
	v_add_u32_e32 v84, s1, v101
	ds_read_b128 v[86:89], v100 offset:36864
	ds_read_b128 v[90:93], v84
	s_ashr_i32 s53, s52, 31
	s_waitcnt lgkmcnt(2)
	v_add_f32_e32 v76, v76, v78
	s_nop 1
	ds_bpermute_b32 v78, v248, v76
	s_waitcnt lgkmcnt(0)
	v_add_f32_e32 v76, v76, v78
	s_nop 1
	ds_bpermute_b32 v78, v247, v76
	s_waitcnt lgkmcnt(0)
	v_add_f32_e32 v76, v76, v78
	s_nop 1
	ds_bpermute_b32 v78, v246, v76
	s_waitcnt lgkmcnt(0)
	v_add_f32_e32 v76, v76, v78
	s_nop 1
	ds_bpermute_b32 v83, v245, v76
	s_waitcnt lgkmcnt(0)
	v_add_f32_e32 v76, v76, v83
	v_xor_b32_e32 v83, 1, v220
	v_cmp_lt_i32_e32 vcc, v83, v77
	s_nop 1
	v_cndmask_b32_e32 v77, v220, v83, vcc
	v_lshlrev_b32_e32 v77, 2, v77
	ds_bpermute_b32 v83, v244, v76
	s_waitcnt lgkmcnt(0)
	v_add_f32_e32 v76, v76, v83
	v_fmamk_f32 v76, v76, 0x3a800000, v218
	v_cmp_gt_f32_e32 vcc, s2, v76
	v_mul_f32_e32 v83, 0x4b800000, v76
	s_lshl_b64 s[2:3], s[52:53], 11
	v_cndmask_b32_e32 v76, v76, v83, vcc
	v_rsq_f32_e32 v76, v76
	s_nop 0
	v_mul_f32_e32 v83, 0x45800000, v76
	v_cndmask_b32_e32 v76, v76, v83, vcc
	v_add_u32_e32 v83, s1, v102
	ds_read_b128 v[94:97], v83
	v_pk_mul_f32 v[46:47], v[46:47], v[76:77] op_sel_hi:[1,0]
	v_pk_mul_f32 v[42:43], v[42:43], v[76:77] op_sel_hi:[1,0]
	v_pk_mul_f32 v[46:47], v[86:87], v[46:47]
	v_pk_add_f32 v[86:87], v[90:91], 1.0 op_sel_hi:[1,0]
	v_pk_mul_f32 v[44:45], v[44:45], v[76:77] op_sel_hi:[1,0]
	s_waitcnt lgkmcnt(0)
	v_pk_fma_f32 v[94:95], v[86:87], v[46:47], v[94:95]
	v_pk_mul_f32 v[46:47], v[48:49], v[76:77] op_sel_hi:[1,0]
	v_pk_add_f32 v[48:49], v[92:93], 1.0 op_sel_hi:[1,0]
	v_pk_mul_f32 v[46:47], v[88:89], v[46:47]
	ds_read_b128 v[86:89], v100
	v_pk_fma_f32 v[92:93], v[48:49], v[46:47], v[96:97]
	v_cvt_pk_bf16_f32 v48, v94, v95
	v_cvt_pk_bf16_f32 v49, v92, v93
	v_lshl_add_u64 v[46:47], v[66:67], 0, s[2:3]
	global_store_dwordx2 v[46:47], v[48:49], off
	s_waitcnt lgkmcnt(0)
	v_pk_mul_f32 v[228:229], v[94:95], v[86:87]
	v_pk_fma_f32 v[228:229], v[92:93], v[88:89], v[228:229]
	ds_read_b128 v[86:89], v100 offset:4096
	v_pk_mul_f32 v[38:39], v[38:39], v[76:77] op_sel_hi:[1,0]
	v_pk_mul_f32 v[34:35], v[34:35], v[76:77] op_sel_hi:[1,0]
	v_pk_mul_f32 v[36:37], v[36:37], v[76:77] op_sel_hi:[1,0]
	s_waitcnt lgkmcnt(0)
	v_pk_mul_f32 v[230:231], v[94:95], v[86:87]
	v_pk_fma_f32 v[230:231], v[92:93], v[88:89], v[230:231]
	ds_read_b128 v[86:89], v100 offset:8192
	s_waitcnt lgkmcnt(0)
	v_pk_mul_f32 v[232:233], v[94:95], v[86:87]
	v_pk_fma_f32 v[232:233], v[92:93], v[88:89], v[232:233]
	ds_read_b128 v[86:89], v100 offset:12288
	s_waitcnt lgkmcnt(0)
	v_pk_mul_f32 v[234:235], v[94:95], v[86:87]
	v_pk_fma_f32 v[234:235], v[92:93], v[88:89], v[234:235]
	ds_read_b128 v[88:91], v100 offset:16384
	s_waitcnt lgkmcnt(0)
	v_pk_mul_f32 v[236:237], v[94:95], v[88:89]
	v_pk_fma_f32 v[236:237], v[92:93], v[90:91], v[236:237]
	ds_read_b128 v[88:91], v100 offset:20480
	s_waitcnt lgkmcnt(0)
	v_pk_mul_f32 v[238:239], v[94:95], v[88:89]
	v_pk_fma_f32 v[238:239], v[92:93], v[90:91], v[238:239]
	ds_read_b128 v[88:91], v100 offset:24576
	s_waitcnt lgkmcnt(0)
	v_pk_mul_f32 v[240:241], v[94:95], v[88:89]
	v_pk_fma_f32 v[240:241], v[92:93], v[90:91], v[240:241]
	ds_read_b128 v[88:91], v100 offset:28672
	s_waitcnt lgkmcnt(0)
	v_pk_mul_f32 v[242:243], v[94:95], v[88:89]
	v_pk_fma_f32 v[242:243], v[92:93], v[90:91], v[242:243]
	ds_read_b128 v[88:91], v100 offset:37888
	ds_read_b128 v[92:95], v84 offset:1024
	ds_read_b128 v[96:99], v83 offset:1024
	s_waitcnt lgkmcnt(2)
	v_pk_mul_f32 v[42:43], v[42:43], v[88:89]
	s_waitcnt lgkmcnt(1)
	v_pk_add_f32 v[88:89], v[92:93], 1.0 op_sel_hi:[1,0]
	v_pk_mul_f32 v[44:45], v[44:45], v[90:91]
	s_waitcnt lgkmcnt(0)
	v_pk_fma_f32 v[42:43], v[42:43], v[88:89], v[96:97]
	v_pk_add_f32 v[88:89], v[94:95], 1.0 op_sel_hi:[1,0]
	s_nop 0
	v_pk_fma_f32 v[44:45], v[44:45], v[88:89], v[98:99]
	v_cvt_pk_bf16_f32 v88, v42, v43
	v_cvt_pk_bf16_f32 v89, v44, v45
	global_store_dwordx2 v[46:47], v[88:89], off offset:512
	ds_read_b128 v[88:91], v100 offset:1024
	s_waitcnt lgkmcnt(0)
	v_pk_fma_f32 v[228:229], v[42:43], v[88:89], v[228:229]
	v_pk_fma_f32 v[228:229], v[44:45], v[90:91], v[228:229]
	ds_read_b128 v[90:93], v100 offset:5120
	s_waitcnt lgkmcnt(0)
	v_pk_fma_f32 v[230:231], v[42:43], v[90:91], v[230:231]
	v_pk_fma_f32 v[230:231], v[44:45], v[92:93], v[230:231]
	ds_read_b128 v[90:93], v100 offset:9216
	s_waitcnt lgkmcnt(0)
	v_pk_fma_f32 v[232:233], v[42:43], v[90:91], v[232:233]
	v_pk_fma_f32 v[232:233], v[44:45], v[92:93], v[232:233]
	ds_read_b128 v[90:93], v100 offset:13312
	s_waitcnt lgkmcnt(0)
	v_pk_fma_f32 v[234:235], v[42:43], v[90:91], v[234:235]
	v_pk_fma_f32 v[234:235], v[44:45], v[92:93], v[234:235]
	ds_read_b128 v[90:93], v100 offset:17408
	s_waitcnt lgkmcnt(0)
	v_pk_fma_f32 v[236:237], v[42:43], v[90:91], v[236:237]
	v_pk_fma_f32 v[236:237], v[44:45], v[92:93], v[236:237]
	ds_read_b128 v[90:93], v100 offset:21504
	s_waitcnt lgkmcnt(0)
	v_pk_fma_f32 v[238:239], v[42:43], v[90:91], v[238:239]
	v_pk_fma_f32 v[238:239], v[44:45], v[92:93], v[238:239]
	ds_read_b128 v[90:93], v100 offset:25600
	s_waitcnt lgkmcnt(0)
	v_pk_fma_f32 v[240:241], v[42:43], v[90:91], v[240:241]
	v_pk_fma_f32 v[240:241], v[44:45], v[92:93], v[240:241]
	ds_read_b128 v[90:93], v100 offset:29696
	s_waitcnt lgkmcnt(0)
	v_pk_fma_f32 v[242:243], v[42:43], v[90:91], v[242:243]
	v_pk_fma_f32 v[242:243], v[44:45], v[92:93], v[242:243]
	ds_read_b128 v[42:45], v100 offset:38912
	ds_read_b128 v[90:93], v84 offset:2048
	ds_read_b128 v[94:97], v83 offset:2048
	s_waitcnt lgkmcnt(2)
	v_pk_mul_f32 v[38:39], v[38:39], v[42:43]
	s_waitcnt lgkmcnt(1)
	v_pk_add_f32 v[42:43], v[90:91], 1.0 op_sel_hi:[1,0]
	s_waitcnt lgkmcnt(0)
	v_pk_fma_f32 v[48:49], v[38:39], v[42:43], v[94:95]
	v_pk_mul_f32 v[38:39], v[40:41], v[76:77] op_sel_hi:[1,0]
	v_pk_add_f32 v[40:41], v[92:93], 1.0 op_sel_hi:[1,0]
	v_pk_mul_f32 v[38:39], v[38:39], v[44:45]
	s_nop 0
	v_pk_fma_f32 v[44:45], v[38:39], v[40:41], v[96:97]
	v_cvt_pk_bf16_f32 v38, v48, v49
	v_cvt_pk_bf16_f32 v39, v44, v45
	global_store_dwordx2 v[46:47], v[38:39], off offset:1024
	ds_read_b128 v[38:41], v100 offset:2048
	s_waitcnt lgkmcnt(0)
	v_pk_fma_f32 v[228:229], v[48:49], v[38:39], v[228:229]
	v_pk_fma_f32 v[228:229], v[44:45], v[40:41], v[228:229]
	ds_read_b128 v[38:41], v100 offset:6144
	s_waitcnt lgkmcnt(0)
	v_pk_fma_f32 v[230:231], v[48:49], v[38:39], v[230:231]
	v_pk_fma_f32 v[230:231], v[44:45], v[40:41], v[230:231]
	ds_read_b128 v[38:41], v100 offset:10240
	s_waitcnt lgkmcnt(0)
	v_pk_fma_f32 v[232:233], v[48:49], v[38:39], v[232:233]
	v_pk_fma_f32 v[232:233], v[44:45], v[40:41], v[232:233]
	ds_read_b128 v[38:41], v100 offset:14336
	s_waitcnt lgkmcnt(0)
	v_pk_fma_f32 v[234:235], v[48:49], v[38:39], v[234:235]
	v_pk_fma_f32 v[234:235], v[44:45], v[40:41], v[234:235]
	ds_read_b128 v[38:41], v100 offset:18432
	s_waitcnt lgkmcnt(0)
	v_pk_fma_f32 v[236:237], v[48:49], v[38:39], v[236:237]
	v_pk_fma_f32 v[236:237], v[44:45], v[40:41], v[236:237]
	ds_read_b128 v[86:89], v100 offset:22528
	s_waitcnt lgkmcnt(0)
	v_pk_fma_f32 v[238:239], v[48:49], v[86:87], v[238:239]
	v_pk_fma_f32 v[238:239], v[44:45], v[88:89], v[238:239]
	ds_read_b128 v[86:89], v100 offset:26624
	s_waitcnt lgkmcnt(0)
	v_pk_fma_f32 v[240:241], v[48:49], v[86:87], v[240:241]
	v_pk_fma_f32 v[240:241], v[44:45], v[88:89], v[240:241]
	ds_read_b128 v[86:89], v100 offset:30720
	s_waitcnt lgkmcnt(0)
	v_pk_fma_f32 v[242:243], v[48:49], v[86:87], v[242:243]
	v_pk_fma_f32 v[242:243], v[44:45], v[88:89], v[242:243]
	ds_read_b128 v[86:89], v100 offset:39936
	ds_read_b128 v[90:93], v84 offset:3072
	ds_read_b128 v[94:97], v83 offset:3072
	s_waitcnt lgkmcnt(2)
	v_pk_mul_f32 v[34:35], v[34:35], v[86:87]
	s_waitcnt lgkmcnt(1)
	v_pk_add_f32 v[44:45], v[90:91], 1.0 op_sel_hi:[1,0]
	v_pk_mul_f32 v[36:37], v[36:37], v[88:89]
	s_waitcnt lgkmcnt(0)
	v_pk_fma_f32 v[34:35], v[34:35], v[44:45], v[94:95]
	v_pk_add_f32 v[44:45], v[92:93], 1.0 op_sel_hi:[1,0]
	s_nop 0
	v_pk_fma_f32 v[36:37], v[36:37], v[44:45], v[96:97]
	v_cvt_pk_bf16_f32 v44, v34, v35
	v_cvt_pk_bf16_f32 v45, v36, v37
	global_store_dwordx2 v[46:47], v[44:45], off offset:1536
	ds_read_b128 v[44:47], v100 offset:3072
	s_waitcnt lgkmcnt(0)
	v_pk_fma_f32 v[228:229], v[34:35], v[44:45], v[228:229]
	v_pk_fma_f32 v[228:229], v[36:37], v[46:47], v[228:229]
	v_add_f32_e32 v43, v228, v229
	ds_read_b128 v[44:47], v100 offset:7168
	s_waitcnt lgkmcnt(0)
	v_pk_fma_f32 v[230:231], v[34:35], v[44:45], v[230:231]
	v_pk_fma_f32 v[230:231], v[36:37], v[46:47], v[230:231]
	v_add_f32_e32 v48, v230, v231
	ds_read_b128 v[44:47], v100 offset:11264
	s_waitcnt lgkmcnt(0)
	v_pk_fma_f32 v[232:233], v[34:35], v[44:45], v[232:233]
	v_pk_fma_f32 v[232:233], v[36:37], v[46:47], v[232:233]
	v_add_f32_e32 v49, v232, v233
	ds_read_b128 v[44:47], v100 offset:15360
	s_waitcnt lgkmcnt(0)
	v_pk_fma_f32 v[234:235], v[34:35], v[44:45], v[234:235]
	v_pk_fma_f32 v[234:235], v[36:37], v[46:47], v[234:235]
	v_add_f32_e32 v42, v234, v235
	ds_read_b128 v[44:47], v100 offset:19456
	s_waitcnt lgkmcnt(0)
	v_pk_fma_f32 v[236:237], v[34:35], v[44:45], v[236:237]
	v_pk_fma_f32 v[236:237], v[36:37], v[46:47], v[236:237]
	v_add_f32_e32 v41, v236, v237
	ds_read_b128 v[44:47], v100 offset:23552
	s_waitcnt lgkmcnt(0)
	v_pk_fma_f32 v[238:239], v[34:35], v[44:45], v[238:239]
	v_pk_fma_f32 v[238:239], v[36:37], v[46:47], v[238:239]
	v_add_f32_e32 v40, v238, v239
	ds_read_b128 v[44:47], v100 offset:27648
	s_waitcnt lgkmcnt(0)
	v_pk_fma_f32 v[240:241], v[34:35], v[44:45], v[240:241]
	v_pk_fma_f32 v[240:241], v[36:37], v[46:47], v[240:241]
	v_add_f32_e32 v39, v240, v241
	ds_read_b128 v[44:47], v100 offset:31744
	s_waitcnt lgkmcnt(0)
	v_mul_f32_e32 v35, v35, v45
	v_fmac_f32_e32 v35, v34, v44
	v_fmac_f32_e32 v35, v36, v46
	v_cndmask_b32_e64 v36, v43, v41, s[40:41]
	v_fmac_f32_e32 v35, v37, v47
	ds_bpermute_b32 v36, v249, v36
	v_cndmask_b32_e64 v37, v48, v40, s[40:41]
	v_add_f32_e32 v34, v242, v35
	v_add_f32_e32 v34, v34, v243
	ds_bpermute_b32 v37, v249, v37
	v_cndmask_b32_e64 v38, v49, v39, s[40:41]
	ds_bpermute_b32 v38, v249, v38
	v_cndmask_b32_e64 v35, v41, v43, s[40:41]
	s_waitcnt lgkmcnt(2)
	v_add_f32_e32 v35, v35, v36
	v_cndmask_b32_e64 v36, v40, v48, s[40:41]
	s_waitcnt lgkmcnt(1)
	v_add_f32_e32 v36, v36, v37
	v_cndmask_b32_e64 v37, v39, v49, s[40:41]
	s_waitcnt lgkmcnt(0)
	v_add_f32_e32 v37, v37, v38
	v_cndmask_b32_e64 v38, v34, v42, s[40:41]
	v_cndmask_b32_e64 v34, v42, v34, s[40:41]
	ds_bpermute_b32 v34, v249, v34
	s_waitcnt lgkmcnt(0)
	v_add_f32_e32 v34, v38, v34
	v_cndmask_b32_e64 v38, v37, v35, s[42:43]
	v_cndmask_b32_e64 v35, v35, v37, s[42:43]
	v_cndmask_b32_e64 v37, v34, v36, s[42:43]
	v_cndmask_b32_e64 v34, v36, v34, s[42:43]
	ds_bpermute_b32 v35, v248, v35
	ds_bpermute_b32 v34, v248, v34
	s_waitcnt lgkmcnt(1)
	v_add_f32_e32 v35, v38, v35
	s_waitcnt lgkmcnt(0)
	v_add_f32_e32 v34, v37, v34
	v_cndmask_b32_e64 v36, v34, v35, s[44:45]
	v_cndmask_b32_e64 v34, v35, v34, s[44:45]
	ds_bpermute_b32 v34, v247, v34
	s_waitcnt lgkmcnt(0)
	v_add_f32_e32 v34, v36, v34
	ds_bpermute_b32 v35, v246, v34
	s_waitcnt lgkmcnt(0)
	v_add_f32_e32 v34, v34, v35
	ds_bpermute_b32 v35, v245, v34
	s_waitcnt lgkmcnt(0)
	v_add_f32_e32 v34, v34, v35
	ds_bpermute_b32 v35, v244, v34
	s_and_saveexec_b64 s[18:19], s[46:47]
	s_cbranch_execz .LBB0_450
	s_lshl_b64 s[2:3], s[52:53], 5
	s_waitcnt lgkmcnt(0)
	v_add_f32_e32 v36, v34, v35
	v_lshl_add_u64 v[34:35], v[64:65], 0, s[2:3]
	global_store_dword v[34:35], v36, off
	s_branch .LBB0_450
